# F1 merge epilogue: running bf16 mix of 6 of 16 accumulator quads kept in free VGPRs across the 4 branch units of a tile (no MIXB reload for br>0, MIXB store only at br==3); same values as baseline
# speedup vs baseline: 1.0137x; 1.0102x over previous
.LBB0_880:
	s_mov_b32 s98, s7
	s_lshl_b32 s22, s7, 11
	s_ashr_i32 s23, s22, 31
	s_cmp_lg_u32 s7, 0
	s_cselect_b64 s[24:25], -1, 0
	s_lshl_b32 s17, s6, 8
	s_lshl_b64 s[22:23], s[22:23], 1
	v_add_u32_e32 v210, s17, v217
	s_add_u32 s22, s39, s22
	v_ashrrev_i32_e32 v211, 31, v210
	s_addc_u32 s23, s40, s23
	v_lshl_or_b32 v208, s49, 8, v222
	v_lshlrev_b64 v[64:65], 14, v[210:211]
	v_lshl_add_u64 v[64:65], s[22:23], 0, v[64:65]
	v_ashrrev_i32_e32 v209, 31, v208
	v_lshl_add_u64 v[64:65], v[208:209], 1, v[64:65]
	global_load_dwordx4 v[188:191], v[64:65], off
	v_lshlrev_b64 v[66:67], 12, v[210:211]
	v_lshl_add_u64 v[66:67], s[10:11], 0, v[66:67]
	s_cmp_eq_u32 s7, 0
	v_lshl_add_u64 v[212:213], v[208:209], 1, v[66:67]
	s_cbranch_scc1 .LBB0_882
.LBB0_882:
	global_load_dwordx4 v[184:187], v[64:65], off offset:256
	v_cndmask_b32_e64 v64, 0, 1, s[24:25]
	v_cmp_ne_u32_e64 s[6:7], 1, v64
	s_andn2_b64 vcc, exec, s[24:25]
	s_cbranch_vccnz .LBB0_884
.LBB0_884:
	v_or_b32_e32 v64, 16, v210
	v_ashrrev_i32_e32 v65, 31, v64
	v_lshlrev_b64 v[66:67], 14, v[64:65]
	v_lshl_add_u64 v[66:67], s[22:23], 0, v[66:67]
	v_lshl_add_u64 v[66:67], v[208:209], 1, v[66:67]
	global_load_dwordx4 v[180:183], v[66:67], off
	v_lshlrev_b64 v[64:65], 12, v[64:65]
	v_lshl_add_u64 v[64:65], s[10:11], 0, v[64:65]
	s_and_b64 vcc, exec, s[6:7]
	v_lshl_add_u64 v[64:65], v[208:209], 1, v[64:65]
	s_cbranch_vccnz .LBB0_886
.LBB0_886:
	global_load_dwordx4 v[176:179], v[66:67], off offset:256
	s_and_b64 vcc, exec, s[6:7]
	s_cbranch_vccnz .LBB0_888
.LBB0_888:
	v_or_b32_e32 v64, 32, v210
	v_ashrrev_i32_e32 v65, 31, v64
	v_lshlrev_b64 v[66:67], 14, v[64:65]
	v_lshl_add_u64 v[66:67], s[22:23], 0, v[66:67]
	v_lshl_add_u64 v[66:67], v[208:209], 1, v[66:67]
	global_load_dwordx4 v[172:175], v[66:67], off
	v_lshlrev_b64 v[64:65], 12, v[64:65]
	v_lshl_add_u64 v[64:65], s[10:11], 0, v[64:65]
	s_and_b64 vcc, exec, s[6:7]
	v_lshl_add_u64 v[64:65], v[208:209], 1, v[64:65]
	s_cbranch_vccnz .LBB0_890
.LBB0_890:
	global_load_dwordx4 v[168:171], v[66:67], off offset:256
	s_and_b64 vcc, exec, s[6:7]
	s_cbranch_vccnz .LBB0_892

.LBB0_896:
	s_waitcnt vmcnt(0)
	v_lshlrev_b32_e32 v214, 16, v188
	v_and_b32_e32 v215, 0xffff0000, v188
	v_lshlrev_b32_e32 v188, 16, v189
	v_and_b32_e32 v189, 0xffff0000, v189
	v_pk_mul_f32 v[158:159], v[158:159], v[188:189]
	v_lshlrev_b32_e32 v188, 16, v190
	v_and_b32_e32 v189, 0xffff0000, v190
	v_pk_mul_f32 v[152:153], v[152:153], v[188:189]
	v_lshlrev_b32_e32 v188, 16, v191
	v_and_b32_e32 v189, 0xffff0000, v191
	v_pk_mul_f32 v[156:157], v[156:157], v[214:215]
	s_and_b64 vcc, exec, s[6:7]
	v_pk_mul_f32 v[154:155], v[154:155], v[188:189]
	s_cbranch_vccnz .LBB0_898
	v_lshlrev_b32_e32 v188, 16, v228
	v_and_b32_e32 v189, 0xffff0000, v228
	v_lshlrev_b32_e32 v190, 16, v229
	v_and_b32_e32 v191, 0xffff0000, v229
	v_lshlrev_b32_e32 v214, 16, v230
	v_and_b32_e32 v215, 0xffff0000, v230
	v_lshlrev_b32_e32 v226, 16, v231
	v_and_b32_e32 v227, 0xffff0000, v231
	v_pk_add_f32 v[158:159], v[158:159], v[190:191]
	v_pk_add_f32 v[156:157], v[156:157], v[188:189]
	v_pk_add_f32 v[154:155], v[154:155], v[226:227]
	v_pk_add_f32 v[152:153], v[152:153], v[214:215]
.LBB0_898:
	v_cvt_pk_bf16_f32 v156, v156, v157
	v_cvt_pk_bf16_f32 v157, v158, v159
	v_cvt_pk_bf16_f32 v158, v152, v153
	v_lshlrev_b32_e32 v152, 16, v184
	v_and_b32_e32 v153, 0xffff0000, v184
	v_pk_mul_f32 v[148:149], v[148:149], v[152:153]
	v_lshlrev_b32_e32 v152, 16, v185
	v_and_b32_e32 v153, 0xffff0000, v185
	v_pk_mul_f32 v[150:151], v[150:151], v[152:153]
	v_lshlrev_b32_e32 v152, 16, v186
	v_and_b32_e32 v153, 0xffff0000, v186
	v_pk_mul_f32 v[144:145], v[144:145], v[152:153]
	v_lshlrev_b32_e32 v152, 16, v187
	v_and_b32_e32 v153, 0xffff0000, v187
	v_cvt_pk_bf16_f32 v159, v154, v155
	s_and_b64 vcc, exec, s[6:7]
	v_pk_mul_f32 v[146:147], v[146:147], v[152:153]
	v_mov_b32_e32 v228, v156
	v_mov_b32_e32 v229, v157
	v_mov_b32_e32 v230, v158
	v_mov_b32_e32 v231, v159
	s_cmp_eq_u32 s98, 3
	s_cbranch_scc0 .Lf1k_6
	global_store_dwordx4 v[212:213], v[156:159], off
.Lf1k_6:
	s_cbranch_vccnz .LBB0_900
	v_lshlrev_b32_e32 v152, 16, v232
	v_and_b32_e32 v153, 0xffff0000, v232
	v_lshlrev_b32_e32 v154, 16, v233
	v_and_b32_e32 v155, 0xffff0000, v233
	v_lshlrev_b32_e32 v156, 16, v234
	v_and_b32_e32 v157, 0xffff0000, v234
	v_lshlrev_b32_e32 v158, 16, v235
	v_and_b32_e32 v159, 0xffff0000, v235
	v_pk_add_f32 v[150:151], v[150:151], v[154:155]
	v_pk_add_f32 v[148:149], v[148:149], v[152:153]
	v_pk_add_f32 v[146:147], v[146:147], v[158:159]
	v_pk_add_f32 v[144:145], v[144:145], v[156:157]
.LBB0_900:
	v_cvt_pk_bf16_f32 v148, v148, v149
	v_cvt_pk_bf16_f32 v149, v150, v151
	v_cvt_pk_bf16_f32 v150, v144, v145
	v_lshlrev_b32_e32 v144, 16, v180
	v_and_b32_e32 v145, 0xffff0000, v180
	v_pk_mul_f32 v[140:141], v[140:141], v[144:145]
	v_lshlrev_b32_e32 v144, 16, v181
	v_and_b32_e32 v145, 0xffff0000, v181
	v_pk_mul_f32 v[142:143], v[142:143], v[144:145]
	v_lshlrev_b32_e32 v144, 16, v182
	v_and_b32_e32 v145, 0xffff0000, v182
	v_pk_mul_f32 v[136:137], v[136:137], v[144:145]
	v_lshlrev_b32_e32 v144, 16, v183
	v_and_b32_e32 v145, 0xffff0000, v183
	v_cvt_pk_bf16_f32 v151, v146, v147
	s_and_b64 vcc, exec, s[6:7]
	v_pk_mul_f32 v[138:139], v[138:139], v[144:145]
	v_mov_b32_e32 v232, v148
	v_mov_b32_e32 v233, v149
	v_mov_b32_e32 v234, v150
	v_mov_b32_e32 v235, v151
	s_cmp_eq_u32 s98, 3
	s_cbranch_scc0 .Lf1k_7
	global_store_dwordx4 v[212:213], v[148:151], off offset:256
.Lf1k_7:
	s_cbranch_vccnz .LBB0_902
	v_lshlrev_b32_e32 v144, 16, v236
	v_and_b32_e32 v145, 0xffff0000, v236
	v_lshlrev_b32_e32 v146, 16, v237
	v_and_b32_e32 v147, 0xffff0000, v237
	v_lshlrev_b32_e32 v148, 16, v238
	v_and_b32_e32 v149, 0xffff0000, v238
	v_lshlrev_b32_e32 v150, 16, v239
	v_and_b32_e32 v151, 0xffff0000, v239
	v_pk_add_f32 v[142:143], v[142:143], v[146:147]
	v_pk_add_f32 v[140:141], v[140:141], v[144:145]
	v_pk_add_f32 v[138:139], v[138:139], v[150:151]
	v_pk_add_f32 v[136:137], v[136:137], v[148:149]
.LBB0_902:
	v_add_u32_e32 v144, s17, v219
	v_cvt_pk_bf16_f32 v140, v140, v141
	v_cvt_pk_bf16_f32 v141, v142, v143
	v_cvt_pk_bf16_f32 v143, v138, v139
	v_lshlrev_b32_e32 v138, 16, v176
	v_and_b32_e32 v139, 0xffff0000, v176
	v_ashrrev_i32_e32 v145, 31, v144
	v_pk_mul_f32 v[128:129], v[128:129], v[138:139]
	v_lshlrev_b32_e32 v138, 16, v177
	v_and_b32_e32 v139, 0xffff0000, v177
	v_cvt_pk_bf16_f32 v142, v136, v137
	v_lshlrev_b64 v[136:137], 12, v[144:145]
	v_pk_mul_f32 v[130:131], v[130:131], v[138:139]
	v_lshlrev_b32_e32 v138, 16, v178
	v_and_b32_e32 v139, 0xffff0000, v178
	v_lshl_add_u64 v[136:137], s[10:11], 0, v[136:137]
	v_pk_mul_f32 v[124:125], v[124:125], v[138:139]
	v_lshlrev_b32_e32 v138, 16, v179
	v_and_b32_e32 v139, 0xffff0000, v179
	v_lshl_add_u64 v[136:137], v[208:209], 1, v[136:137]
	s_and_b64 vcc, exec, s[6:7]
	v_pk_mul_f32 v[126:127], v[126:127], v[138:139]
	v_mov_b32_e32 v236, v140
	v_mov_b32_e32 v237, v141
	v_mov_b32_e32 v238, v142
	v_mov_b32_e32 v239, v143
	s_cmp_eq_u32 s98, 3
	s_cbranch_scc0 .Lf1k_8
	global_store_dwordx4 v[136:137], v[140:143], off
.Lf1k_8:
	s_cbranch_vccnz .LBB0_904
	v_lshlrev_b32_e32 v138, 16, v240
	v_and_b32_e32 v139, 0xffff0000, v240
	v_lshlrev_b32_e32 v140, 16, v241
	v_and_b32_e32 v141, 0xffff0000, v241
	v_lshlrev_b32_e32 v142, 16, v242
	v_and_b32_e32 v143, 0xffff0000, v242
	v_lshlrev_b32_e32 v144, 16, v243
	v_and_b32_e32 v145, 0xffff0000, v243
	v_pk_add_f32 v[130:131], v[130:131], v[140:141]
	v_pk_add_f32 v[128:129], v[128:129], v[138:139]
	v_pk_add_f32 v[126:127], v[126:127], v[144:145]
	v_pk_add_f32 v[124:125], v[124:125], v[142:143]
.LBB0_904:
	v_cvt_pk_bf16_f32 v128, v128, v129
	v_cvt_pk_bf16_f32 v129, v130, v131
	v_cvt_pk_bf16_f32 v130, v124, v125
	v_lshlrev_b32_e32 v124, 16, v172
	v_and_b32_e32 v125, 0xffff0000, v172
	v_pk_mul_f32 v[116:117], v[116:117], v[124:125]
	v_lshlrev_b32_e32 v124, 16, v173
	v_and_b32_e32 v125, 0xffff0000, v173
	v_pk_mul_f32 v[118:119], v[118:119], v[124:125]
	v_lshlrev_b32_e32 v124, 16, v174
	v_and_b32_e32 v125, 0xffff0000, v174
	v_pk_mul_f32 v[112:113], v[112:113], v[124:125]
	v_lshlrev_b32_e32 v124, 16, v175
	v_and_b32_e32 v125, 0xffff0000, v175
	v_cvt_pk_bf16_f32 v131, v126, v127
	s_and_b64 vcc, exec, s[6:7]
	v_pk_mul_f32 v[114:115], v[114:115], v[124:125]
	v_mov_b32_e32 v240, v128
	v_mov_b32_e32 v241, v129
	v_mov_b32_e32 v242, v130
	v_mov_b32_e32 v243, v131
	s_cmp_eq_u32 s98, 3
	s_cbranch_scc0 .Lf1k_9
	global_store_dwordx4 v[136:137], v[128:131], off offset:256
.Lf1k_9:
	s_cbranch_vccnz .LBB0_906
	v_lshlrev_b32_e32 v124, 16, v244
	v_and_b32_e32 v125, 0xffff0000, v244
	v_lshlrev_b32_e32 v126, 16, v245
	v_and_b32_e32 v127, 0xffff0000, v245
	v_lshlrev_b32_e32 v128, 16, v246
	v_and_b32_e32 v129, 0xffff0000, v246
	v_lshlrev_b32_e32 v130, 16, v247
	v_and_b32_e32 v131, 0xffff0000, v247
	v_pk_add_f32 v[118:119], v[118:119], v[126:127]
	v_pk_add_f32 v[116:117], v[116:117], v[124:125]
	v_pk_add_f32 v[114:115], v[114:115], v[130:131]
	v_pk_add_f32 v[112:113], v[112:113], v[128:129]
.LBB0_906:
	v_add_u32_e32 v124, s17, v220
	v_cvt_pk_bf16_f32 v116, v116, v117
	v_cvt_pk_bf16_f32 v117, v118, v119
	v_cvt_pk_bf16_f32 v119, v114, v115
	v_lshlrev_b32_e32 v114, 16, v168
	v_and_b32_e32 v115, 0xffff0000, v168
	v_ashrrev_i32_e32 v125, 31, v124
	v_pk_mul_f32 v[104:105], v[104:105], v[114:115]
	v_lshlrev_b32_e32 v114, 16, v169
	v_and_b32_e32 v115, 0xffff0000, v169
	v_cvt_pk_bf16_f32 v118, v112, v113
	v_lshlrev_b64 v[112:113], 12, v[124:125]
	v_pk_mul_f32 v[106:107], v[106:107], v[114:115]
	v_lshlrev_b32_e32 v114, 16, v170
	v_and_b32_e32 v115, 0xffff0000, v170
	v_lshl_add_u64 v[112:113], s[10:11], 0, v[112:113]
	v_pk_mul_f32 v[96:97], v[96:97], v[114:115]
	v_lshlrev_b32_e32 v114, 16, v171
	v_and_b32_e32 v115, 0xffff0000, v171
	v_lshl_add_u64 v[112:113], v[208:209], 1, v[112:113]
	s_and_b64 vcc, exec, s[6:7]
	v_pk_mul_f32 v[98:99], v[98:99], v[114:115]
	v_mov_b32_e32 v244, v116
	v_mov_b32_e32 v245, v117
	v_mov_b32_e32 v246, v118
	v_mov_b32_e32 v247, v119
	s_cmp_eq_u32 s98, 3
	s_cbranch_scc0 .Lf1k_10
	global_store_dwordx4 v[112:113], v[116:119], off
.Lf1k_10:
	s_cbranch_vccnz .LBB0_908
	v_lshlrev_b32_e32 v114, 16, v248
	v_and_b32_e32 v115, 0xffff0000, v248
	v_lshlrev_b32_e32 v116, 16, v249
	v_and_b32_e32 v117, 0xffff0000, v249
	v_lshlrev_b32_e32 v118, 16, v250
	v_and_b32_e32 v119, 0xffff0000, v250
	v_lshlrev_b32_e32 v124, 16, v251
	v_and_b32_e32 v125, 0xffff0000, v251
	v_pk_add_f32 v[106:107], v[106:107], v[116:117]
	v_pk_add_f32 v[104:105], v[104:105], v[114:115]
	v_pk_add_f32 v[98:99], v[98:99], v[124:125]
	v_pk_add_f32 v[96:97], v[96:97], v[118:119]
.LBB0_908:
	v_cvt_pk_bf16_f32 v104, v104, v105
	v_cvt_pk_bf16_f32 v105, v106, v107
	v_cvt_pk_bf16_f32 v106, v96, v97
	v_lshlrev_b32_e32 v96, 16, v164
	v_and_b32_e32 v97, 0xffff0000, v164
	v_pk_mul_f32 v[92:93], v[92:93], v[96:97]
	v_lshlrev_b32_e32 v96, 16, v165
	v_and_b32_e32 v97, 0xffff0000, v165
	v_pk_mul_f32 v[94:95], v[94:95], v[96:97]
	v_lshlrev_b32_e32 v96, 16, v166
	v_and_b32_e32 v97, 0xffff0000, v166
	v_pk_mul_f32 v[84:85], v[84:85], v[96:97]
	v_lshlrev_b32_e32 v96, 16, v167
	v_and_b32_e32 v97, 0xffff0000, v167
	v_cvt_pk_bf16_f32 v107, v98, v99
	s_and_b64 vcc, exec, s[6:7]
	v_pk_mul_f32 v[86:87], v[86:87], v[96:97]
	v_mov_b32_e32 v248, v104
	v_mov_b32_e32 v249, v105
	v_mov_b32_e32 v250, v106
	v_mov_b32_e32 v251, v107
	s_cmp_eq_u32 s98, 3
	s_cbranch_scc0 .Lf1k_11
	global_store_dwordx4 v[112:113], v[104:107], off offset:256
.Lf1k_11:
	s_cbranch_vccnz .LBB0_910
	v_lshlrev_b32_e32 v96, 16, v68
	v_and_b32_e32 v97, 0xffff0000, v68
	v_lshlrev_b32_e32 v98, 16, v69
	v_and_b32_e32 v99, 0xffff0000, v69
	v_lshlrev_b32_e32 v104, 16, v70
	v_and_b32_e32 v105, 0xffff0000, v70
	v_lshlrev_b32_e32 v106, 16, v71
	v_and_b32_e32 v107, 0xffff0000, v71
	v_pk_add_f32 v[94:95], v[94:95], v[98:99]
	v_pk_add_f32 v[92:93], v[92:93], v[96:97]
	v_pk_add_f32 v[86:87], v[86:87], v[106:107]
	v_pk_add_f32 v[84:85], v[84:85], v[104:105]
